# LayerNorm phases, sample rows: per-16B chains of (load, vmcnt(0), add) over the K-split partials re-ordered into batched loads + one wait (same f32 adds, same order)
# speedup vs baseline: 1.1189x; 1.0151x over previous
.LBB0_1535:
	v_add_u32_e32 v96, 0xffffe000, v117
	v_lshlrev_b64 v[64:65], 11, v[96:97]
	v_or_b32_e32 v64, v64, v98
	v_readlane_b32 s36, v253, 21
	s_movk_i32 s0, 0x1fff
	v_lshlrev_b64 v[104:105], 2, v[64:65]
	v_readlane_b32 s38, v253, 23
	v_readlane_b32 s39, v253, 24
	v_cmp_lt_i32_e64 s[0:1], s0, v117
	v_readlane_b32 s37, v253, 22
	v_lshl_add_u64 v[80:81], s[38:39], 0, v[104:105]
	v_readlane_b32 s40, v253, 25
	v_readlane_b32 s41, v253, 26
	v_readlane_b32 s42, v253, 27
	v_readlane_b32 s43, v253, 28
	v_readlane_b32 s44, v253, 29
	v_readlane_b32 s45, v253, 30
	v_readlane_b32 s46, v253, 31
	v_readlane_b32 s47, v253, 32
	v_readlane_b32 s48, v253, 33
	v_readlane_b32 s49, v253, 34
	v_readlane_b32 s50, v253, 35
	v_readlane_b32 s51, v253, 36
	s_and_saveexec_b64 s[12:13], s[0:1]
	s_xor_b64 s[12:13], exec, s[12:13]
	s_cbranch_execz .LBB0_1537
	v_lshl_add_u64 v[72:73], s[92:93], 0, v[104:105]
	global_load_dwordx4 v[64:67], v[80:81], off
	global_load_dwordx4 v[148:151], v[72:73], off
	v_add_co_u32_e32 v146, vcc, 0x200000, v72
	s_nop 1
	v_addc_co_u32_e32 v147, vcc, 0, v73, vcc
	global_load_dwordx4 v[152:155], v[146:147], off
	v_add_co_u32_e32 v146, vcc, 0x400000, v72
	s_nop 1
	v_addc_co_u32_e32 v147, vcc, 0, v73, vcc
	global_load_dwordx4 v[156:159], v[146:147], off
	v_add_co_u32_e32 v146, vcc, 0x600000, v72
	s_nop 1
	v_addc_co_u32_e32 v147, vcc, 0, v73, vcc
	global_load_dwordx4 v[160:163], v[146:147], off
	v_add_co_u32_e32 v146, vcc, 0x800000, v72
	s_nop 1
	v_addc_co_u32_e32 v147, vcc, 0, v73, vcc
	global_load_dwordx4 v[164:167], v[146:147], off
	v_add_co_u32_e32 v146, vcc, 0xa00000, v72
	s_nop 1
	v_addc_co_u32_e32 v147, vcc, 0, v73, vcc
	global_load_dwordx4 v[168:171], v[146:147], off
	v_add_co_u32_e32 v146, vcc, 0xc00000, v72
	s_nop 1
	v_addc_co_u32_e32 v147, vcc, 0, v73, vcc
	global_load_dwordx4 v[172:175], v[146:147], off
	v_add_co_u32_e32 v146, vcc, 0xe00000, v72
	s_nop 1
	v_addc_co_u32_e32 v147, vcc, 0, v73, vcc
	global_load_dwordx4 v[176:179], v[146:147], off
	s_waitcnt vmcnt(0)
	v_pk_fma_f32 v[68:69], v[64:65], s[6:7], v[148:149] op_sel_hi:[1,0,1]
	v_pk_fma_f32 v[70:71], v[66:67], s[6:7], v[150:151] op_sel_hi:[1,0,1]
	v_pk_add_f32 v[68:69], v[68:69], v[152:153]
	v_pk_add_f32 v[70:71], v[70:71], v[154:155]
	v_pk_add_f32 v[68:69], v[68:69], v[156:157]
	v_pk_add_f32 v[70:71], v[70:71], v[158:159]
	v_pk_add_f32 v[68:69], v[68:69], v[160:161]
	v_pk_add_f32 v[70:71], v[70:71], v[162:163]
	v_pk_add_f32 v[68:69], v[68:69], v[164:165]
	v_pk_add_f32 v[70:71], v[70:71], v[166:167]
	v_pk_add_f32 v[68:69], v[68:69], v[168:169]
	v_pk_add_f32 v[70:71], v[70:71], v[170:171]
	v_pk_add_f32 v[68:69], v[68:69], v[172:173]
	v_pk_add_f32 v[70:71], v[70:71], v[174:175]
	v_pk_add_f32 v[66:67], v[70:71], v[178:179]
	v_pk_add_f32 v[64:65], v[68:69], v[176:177]
	s_or_saveexec_b64 s[12:13], s[12:13]
	v_lshl_add_u64 v[106:107], s[96:97], 0, v[100:101]
	s_xor_b64 exec, exec, s[12:13]
	s_cbranch_execz .LBB0_1539
	s_branch .LBB0_1538

.LBB0_1539:
	s_or_b64 exec, exec, s[12:13]
	s_and_saveexec_b64 s[12:13], s[0:1]
	s_xor_b64 s[12:13], exec, s[12:13]
	s_cbranch_execz .LBB0_1541
	v_or_b32_e32 v72, 0x400, v104
	v_mov_b32_e32 v73, v105
	v_lshl_add_u64 v[76:77], s[92:93], 0, v[72:73]
	global_load_dwordx4 v[68:71], v[80:81], off offset:1024
	global_load_dwordx4 v[148:151], v[76:77], off
	v_add_co_u32_e32 v146, vcc, 0x200000, v76
	s_nop 1
	v_addc_co_u32_e32 v147, vcc, 0, v77, vcc
	global_load_dwordx4 v[152:155], v[146:147], off
	v_add_co_u32_e32 v146, vcc, 0x400000, v76
	s_nop 1
	v_addc_co_u32_e32 v147, vcc, 0, v77, vcc
	global_load_dwordx4 v[156:159], v[146:147], off
	v_add_co_u32_e32 v146, vcc, 0x600000, v76
	s_nop 1
	v_addc_co_u32_e32 v147, vcc, 0, v77, vcc
	global_load_dwordx4 v[160:163], v[146:147], off
	v_add_co_u32_e32 v146, vcc, 0x800000, v76
	s_nop 1
	v_addc_co_u32_e32 v147, vcc, 0, v77, vcc
	global_load_dwordx4 v[164:167], v[146:147], off
	v_add_co_u32_e32 v146, vcc, 0xa00000, v76
	s_nop 1
	v_addc_co_u32_e32 v147, vcc, 0, v77, vcc
	global_load_dwordx4 v[168:171], v[146:147], off
	v_add_co_u32_e32 v146, vcc, 0xc00000, v76
	s_nop 1
	v_addc_co_u32_e32 v147, vcc, 0, v77, vcc
	global_load_dwordx4 v[172:175], v[146:147], off
	v_add_co_u32_e32 v146, vcc, 0xe00000, v76
	s_nop 1
	v_addc_co_u32_e32 v147, vcc, 0, v77, vcc
	global_load_dwordx4 v[176:179], v[146:147], off
	s_waitcnt vmcnt(0)
	v_pk_fma_f32 v[72:73], v[68:69], s[6:7], v[148:149] op_sel_hi:[1,0,1]
	v_pk_fma_f32 v[74:75], v[70:71], s[6:7], v[150:151] op_sel_hi:[1,0,1]
	v_pk_add_f32 v[72:73], v[72:73], v[152:153]
	v_pk_add_f32 v[74:75], v[74:75], v[154:155]
	v_pk_add_f32 v[72:73], v[72:73], v[156:157]
	v_pk_add_f32 v[74:75], v[74:75], v[158:159]
	v_pk_add_f32 v[72:73], v[72:73], v[160:161]
	v_pk_add_f32 v[74:75], v[74:75], v[162:163]
	v_pk_add_f32 v[72:73], v[72:73], v[164:165]
	v_pk_add_f32 v[74:75], v[74:75], v[166:167]
	v_pk_add_f32 v[72:73], v[72:73], v[168:169]
	v_pk_add_f32 v[74:75], v[74:75], v[170:171]
	v_pk_add_f32 v[72:73], v[72:73], v[172:173]
	v_pk_add_f32 v[74:75], v[74:75], v[174:175]
	v_pk_add_f32 v[70:71], v[74:75], v[178:179]
	v_pk_add_f32 v[68:69], v[72:73], v[176:177]
	s_andn2_saveexec_b64 s[12:13], s[12:13]
	s_cbranch_execz .LBB0_1543
	s_branch .LBB0_1542

.LBB0_1543:
	s_or_b64 exec, exec, s[12:13]
	s_and_saveexec_b64 s[12:13], s[0:1]
	s_xor_b64 s[12:13], exec, s[12:13]
	s_cbranch_execz .LBB0_1545
	v_or_b32_e32 v76, 0x800, v104
	v_mov_b32_e32 v77, v105
	v_lshl_add_u64 v[82:83], s[92:93], 0, v[76:77]
	global_load_dwordx4 v[72:75], v[80:81], off offset:2048
	global_load_dwordx4 v[148:151], v[82:83], off
	v_add_co_u32_e32 v146, vcc, 0x200000, v82
	s_nop 1
	v_addc_co_u32_e32 v147, vcc, 0, v83, vcc
	global_load_dwordx4 v[152:155], v[146:147], off
	v_add_co_u32_e32 v146, vcc, 0x400000, v82
	s_nop 1
	v_addc_co_u32_e32 v147, vcc, 0, v83, vcc
	global_load_dwordx4 v[156:159], v[146:147], off
	v_add_co_u32_e32 v146, vcc, 0x600000, v82
	s_nop 1
	v_addc_co_u32_e32 v147, vcc, 0, v83, vcc
	global_load_dwordx4 v[160:163], v[146:147], off
	v_add_co_u32_e32 v146, vcc, 0x800000, v82
	s_nop 1
	v_addc_co_u32_e32 v147, vcc, 0, v83, vcc
	global_load_dwordx4 v[164:167], v[146:147], off
	v_add_co_u32_e32 v146, vcc, 0xa00000, v82
	s_nop 1
	v_addc_co_u32_e32 v147, vcc, 0, v83, vcc
	global_load_dwordx4 v[168:171], v[146:147], off
	v_add_co_u32_e32 v146, vcc, 0xc00000, v82
	s_nop 1
	v_addc_co_u32_e32 v147, vcc, 0, v83, vcc
	global_load_dwordx4 v[172:175], v[146:147], off
	v_add_co_u32_e32 v146, vcc, 0xe00000, v82
	s_nop 1
	v_addc_co_u32_e32 v147, vcc, 0, v83, vcc
	global_load_dwordx4 v[176:179], v[146:147], off
	s_waitcnt vmcnt(0)
	v_pk_fma_f32 v[76:77], v[72:73], s[6:7], v[148:149] op_sel_hi:[1,0,1]
	v_pk_fma_f32 v[78:79], v[74:75], s[6:7], v[150:151] op_sel_hi:[1,0,1]
	v_pk_add_f32 v[76:77], v[76:77], v[152:153]
	v_pk_add_f32 v[78:79], v[78:79], v[154:155]
	v_pk_add_f32 v[76:77], v[76:77], v[156:157]
	v_pk_add_f32 v[78:79], v[78:79], v[158:159]
	v_pk_add_f32 v[76:77], v[76:77], v[160:161]
	v_pk_add_f32 v[78:79], v[78:79], v[162:163]
	v_pk_add_f32 v[76:77], v[76:77], v[164:165]
	v_pk_add_f32 v[78:79], v[78:79], v[166:167]
	v_pk_add_f32 v[76:77], v[76:77], v[168:169]
	v_pk_add_f32 v[78:79], v[78:79], v[170:171]
	v_pk_add_f32 v[76:77], v[76:77], v[172:173]
	v_pk_add_f32 v[78:79], v[78:79], v[174:175]
	v_pk_add_f32 v[74:75], v[78:79], v[178:179]
	v_pk_add_f32 v[72:73], v[76:77], v[176:177]
	s_andn2_saveexec_b64 s[12:13], s[12:13]
	s_cbranch_execz .LBB0_1547
	s_branch .LBB0_1546

.LBB0_1547:
	s_or_b64 exec, exec, s[12:13]
	s_and_saveexec_b64 s[12:13], s[0:1]
	s_xor_b64 s[12:13], exec, s[12:13]
	s_cbranch_execz .LBB0_1549
	global_load_dwordx4 v[76:79], v[80:81], off offset:3072
	v_or_b32_e32 v80, 0xc00, v104
	v_mov_b32_e32 v81, v105
	v_lshl_add_u64 v[84:85], s[92:93], 0, v[80:81]
	global_load_dwordx4 v[148:151], v[84:85], off
	v_add_co_u32_e32 v146, vcc, 0x200000, v84
	s_nop 1
	v_addc_co_u32_e32 v147, vcc, 0, v85, vcc
	global_load_dwordx4 v[152:155], v[146:147], off
	v_add_co_u32_e32 v146, vcc, 0x400000, v84
	s_nop 1
	v_addc_co_u32_e32 v147, vcc, 0, v85, vcc
	global_load_dwordx4 v[156:159], v[146:147], off
	v_add_co_u32_e32 v146, vcc, 0x600000, v84
	s_nop 1
	v_addc_co_u32_e32 v147, vcc, 0, v85, vcc
	global_load_dwordx4 v[160:163], v[146:147], off
	v_add_co_u32_e32 v146, vcc, 0x800000, v84
	s_nop 1
	v_addc_co_u32_e32 v147, vcc, 0, v85, vcc
	global_load_dwordx4 v[164:167], v[146:147], off
	v_add_co_u32_e32 v146, vcc, 0xa00000, v84
	s_nop 1
	v_addc_co_u32_e32 v147, vcc, 0, v85, vcc
	global_load_dwordx4 v[168:171], v[146:147], off
	v_add_co_u32_e32 v146, vcc, 0xc00000, v84
	s_nop 1
	v_addc_co_u32_e32 v147, vcc, 0, v85, vcc
	global_load_dwordx4 v[172:175], v[146:147], off
	v_add_co_u32_e32 v146, vcc, 0xe00000, v84
	s_nop 1
	v_addc_co_u32_e32 v147, vcc, 0, v85, vcc
	global_load_dwordx4 v[176:179], v[146:147], off
	s_waitcnt vmcnt(0)
	v_pk_fma_f32 v[80:81], v[76:77], s[6:7], v[148:149] op_sel_hi:[1,0,1]
	v_pk_fma_f32 v[82:83], v[78:79], s[6:7], v[150:151] op_sel_hi:[1,0,1]
	v_pk_add_f32 v[80:81], v[80:81], v[152:153]
	v_pk_add_f32 v[82:83], v[82:83], v[154:155]
	v_pk_add_f32 v[80:81], v[80:81], v[156:157]
	v_pk_add_f32 v[82:83], v[82:83], v[158:159]
	v_pk_add_f32 v[80:81], v[80:81], v[160:161]
	v_pk_add_f32 v[82:83], v[82:83], v[162:163]
	v_pk_add_f32 v[80:81], v[80:81], v[164:165]
	v_pk_add_f32 v[82:83], v[82:83], v[166:167]
	v_pk_add_f32 v[80:81], v[80:81], v[168:169]
	v_pk_add_f32 v[82:83], v[82:83], v[170:171]
	v_pk_add_f32 v[80:81], v[80:81], v[172:173]
	v_pk_add_f32 v[82:83], v[82:83], v[174:175]
	v_pk_add_f32 v[78:79], v[82:83], v[178:179]
	v_pk_add_f32 v[76:77], v[80:81], v[176:177]
	s_andn2_saveexec_b64 s[12:13], s[12:13]
	s_cbranch_execz .LBB0_1551
	s_branch .LBB0_1550

.LBB0_1551:
	s_or_b64 exec, exec, s[12:13]
	s_and_saveexec_b64 s[12:13], s[0:1]
	s_xor_b64 s[12:13], exec, s[12:13]
	s_cbranch_execz .LBB0_1553
	v_readlane_b32 s36, v253, 21
	v_or_b32_e32 v84, 0x1000, v104
	v_mov_b32_e32 v85, v105
	v_readlane_b32 s38, v253, 23
	v_readlane_b32 s39, v253, 24
	v_lshl_add_u64 v[88:89], s[92:93], 0, v[84:85]
	v_readlane_b32 s37, v253, 22
	v_lshl_add_u64 v[80:81], s[38:39], 0, v[84:85]
	global_load_dwordx4 v[80:83], v[80:81], off
	global_load_dwordx4 v[148:151], v[88:89], off
	v_add_co_u32_e32 v146, vcc, 0x200000, v88
	s_nop 1
	v_addc_co_u32_e32 v147, vcc, 0, v89, vcc
	global_load_dwordx4 v[152:155], v[146:147], off
	v_add_co_u32_e32 v146, vcc, 0x400000, v88
	s_nop 1
	v_addc_co_u32_e32 v147, vcc, 0, v89, vcc
	global_load_dwordx4 v[156:159], v[146:147], off
	v_add_co_u32_e32 v146, vcc, 0x600000, v88
	s_nop 1
	v_addc_co_u32_e32 v147, vcc, 0, v89, vcc
	global_load_dwordx4 v[160:163], v[146:147], off
	v_add_co_u32_e32 v146, vcc, 0x800000, v88
	s_nop 1
	v_addc_co_u32_e32 v147, vcc, 0, v89, vcc
	global_load_dwordx4 v[164:167], v[146:147], off
	v_add_co_u32_e32 v146, vcc, 0xa00000, v88
	s_nop 1
	v_addc_co_u32_e32 v147, vcc, 0, v89, vcc
	global_load_dwordx4 v[168:171], v[146:147], off
	v_add_co_u32_e32 v146, vcc, 0xc00000, v88
	s_nop 1
	v_addc_co_u32_e32 v147, vcc, 0, v89, vcc
	global_load_dwordx4 v[172:175], v[146:147], off
	v_add_co_u32_e32 v146, vcc, 0xe00000, v88
	s_nop 1
	v_addc_co_u32_e32 v147, vcc, 0, v89, vcc
	global_load_dwordx4 v[176:179], v[146:147], off
	s_waitcnt vmcnt(0)
	v_readlane_b32 s40, v253, 25
	v_readlane_b32 s41, v253, 26
	v_readlane_b32 s42, v253, 27
	v_readlane_b32 s43, v253, 28
	v_readlane_b32 s44, v253, 29
	v_readlane_b32 s45, v253, 30
	v_readlane_b32 s46, v253, 31
	v_readlane_b32 s47, v253, 32
	v_readlane_b32 s48, v253, 33
	v_readlane_b32 s49, v253, 34
	v_readlane_b32 s50, v253, 35
	v_readlane_b32 s51, v253, 36
	v_pk_fma_f32 v[84:85], v[80:81], s[6:7], v[148:149] op_sel_hi:[1,0,1]
	v_pk_fma_f32 v[86:87], v[82:83], s[6:7], v[150:151] op_sel_hi:[1,0,1]
	v_pk_add_f32 v[84:85], v[84:85], v[152:153]
	v_pk_add_f32 v[86:87], v[86:87], v[154:155]
	v_pk_add_f32 v[84:85], v[84:85], v[156:157]
	v_pk_add_f32 v[86:87], v[86:87], v[158:159]
	v_pk_add_f32 v[84:85], v[84:85], v[160:161]
	v_pk_add_f32 v[86:87], v[86:87], v[162:163]
	v_pk_add_f32 v[84:85], v[84:85], v[164:165]
	v_pk_add_f32 v[86:87], v[86:87], v[166:167]
	v_pk_add_f32 v[84:85], v[84:85], v[168:169]
	v_pk_add_f32 v[86:87], v[86:87], v[170:171]
	v_pk_add_f32 v[84:85], v[84:85], v[172:173]
	v_pk_add_f32 v[86:87], v[86:87], v[174:175]
	v_pk_add_f32 v[82:83], v[86:87], v[178:179]
	v_pk_add_f32 v[80:81], v[84:85], v[176:177]
	s_andn2_saveexec_b64 s[12:13], s[12:13]
	s_cbranch_execz .LBB0_1555
	s_branch .LBB0_1554

.LBB0_1555:
	s_or_b64 exec, exec, s[12:13]
	s_and_saveexec_b64 s[12:13], s[0:1]
	s_xor_b64 s[12:13], exec, s[12:13]
	s_cbranch_execz .LBB0_1557
	v_readlane_b32 s36, v253, 21
	v_or_b32_e32 v88, 0x1400, v104
	v_mov_b32_e32 v89, v105
	v_readlane_b32 s38, v253, 23
	v_readlane_b32 s39, v253, 24
	v_lshl_add_u64 v[92:93], s[92:93], 0, v[88:89]
	v_readlane_b32 s37, v253, 22
	v_lshl_add_u64 v[84:85], s[38:39], 0, v[88:89]
	global_load_dwordx4 v[84:87], v[84:85], off
	global_load_dwordx4 v[148:151], v[92:93], off
	v_add_co_u32_e32 v146, vcc, 0x200000, v92
	s_nop 1
	v_addc_co_u32_e32 v147, vcc, 0, v93, vcc
	global_load_dwordx4 v[152:155], v[146:147], off
	v_add_co_u32_e32 v146, vcc, 0x400000, v92
	s_nop 1
	v_addc_co_u32_e32 v147, vcc, 0, v93, vcc
	global_load_dwordx4 v[156:159], v[146:147], off
	v_add_co_u32_e32 v146, vcc, 0x600000, v92
	s_nop 1
	v_addc_co_u32_e32 v147, vcc, 0, v93, vcc
	global_load_dwordx4 v[160:163], v[146:147], off
	v_add_co_u32_e32 v146, vcc, 0x800000, v92
	s_nop 1
	v_addc_co_u32_e32 v147, vcc, 0, v93, vcc
	global_load_dwordx4 v[164:167], v[146:147], off
	v_add_co_u32_e32 v146, vcc, 0xa00000, v92
	s_nop 1
	v_addc_co_u32_e32 v147, vcc, 0, v93, vcc
	global_load_dwordx4 v[168:171], v[146:147], off
	v_add_co_u32_e32 v146, vcc, 0xc00000, v92
	s_nop 1
	v_addc_co_u32_e32 v147, vcc, 0, v93, vcc
	global_load_dwordx4 v[172:175], v[146:147], off
	v_add_co_u32_e32 v146, vcc, 0xe00000, v92
	s_nop 1
	v_addc_co_u32_e32 v147, vcc, 0, v93, vcc
	global_load_dwordx4 v[176:179], v[146:147], off
	s_waitcnt vmcnt(0)
	v_readlane_b32 s40, v253, 25
	v_readlane_b32 s41, v253, 26
	v_readlane_b32 s42, v253, 27
	v_readlane_b32 s43, v253, 28
	v_readlane_b32 s44, v253, 29
	v_readlane_b32 s45, v253, 30
	v_readlane_b32 s46, v253, 31
	v_readlane_b32 s47, v253, 32
	v_readlane_b32 s48, v253, 33
	v_readlane_b32 s49, v253, 34
	v_readlane_b32 s50, v253, 35
	v_readlane_b32 s51, v253, 36
	v_pk_fma_f32 v[88:89], v[84:85], s[6:7], v[148:149] op_sel_hi:[1,0,1]
	v_pk_fma_f32 v[90:91], v[86:87], s[6:7], v[150:151] op_sel_hi:[1,0,1]
	v_pk_add_f32 v[88:89], v[88:89], v[152:153]
	v_pk_add_f32 v[90:91], v[90:91], v[154:155]
	v_pk_add_f32 v[88:89], v[88:89], v[156:157]
	v_pk_add_f32 v[90:91], v[90:91], v[158:159]
	v_pk_add_f32 v[88:89], v[88:89], v[160:161]
	v_pk_add_f32 v[90:91], v[90:91], v[162:163]
	v_pk_add_f32 v[88:89], v[88:89], v[164:165]
	v_pk_add_f32 v[90:91], v[90:91], v[166:167]
	v_pk_add_f32 v[88:89], v[88:89], v[168:169]
	v_pk_add_f32 v[90:91], v[90:91], v[170:171]
	v_pk_add_f32 v[88:89], v[88:89], v[172:173]
	v_pk_add_f32 v[90:91], v[90:91], v[174:175]
	v_pk_add_f32 v[86:87], v[90:91], v[178:179]
	v_pk_add_f32 v[84:85], v[88:89], v[176:177]
	s_andn2_saveexec_b64 s[12:13], s[12:13]
	s_cbranch_execz .LBB0_1559
	s_branch .LBB0_1558

.LBB0_1559:
	s_or_b64 exec, exec, s[12:13]
	s_and_saveexec_b64 s[12:13], s[0:1]
	s_xor_b64 s[12:13], exec, s[12:13]
	s_cbranch_execz .LBB0_1561
	v_readlane_b32 s36, v253, 21
	v_or_b32_e32 v92, 0x1800, v104
	v_mov_b32_e32 v93, v105
	v_readlane_b32 s38, v253, 23
	v_readlane_b32 s39, v253, 24
	v_lshl_add_u64 v[124:125], s[92:93], 0, v[92:93]
	v_readlane_b32 s37, v253, 22
	v_lshl_add_u64 v[88:89], s[38:39], 0, v[92:93]
	global_load_dwordx4 v[88:91], v[88:89], off
	global_load_dwordx4 v[148:151], v[124:125], off
	v_add_co_u32_e32 v146, vcc, 0x200000, v124
	s_nop 1
	v_addc_co_u32_e32 v147, vcc, 0, v125, vcc
	global_load_dwordx4 v[152:155], v[146:147], off
	v_add_co_u32_e32 v146, vcc, 0x400000, v124
	s_nop 1
	v_addc_co_u32_e32 v147, vcc, 0, v125, vcc
	global_load_dwordx4 v[156:159], v[146:147], off
	v_add_co_u32_e32 v146, vcc, 0x600000, v124
	s_nop 1
	v_addc_co_u32_e32 v147, vcc, 0, v125, vcc
	global_load_dwordx4 v[160:163], v[146:147], off
	v_add_co_u32_e32 v146, vcc, 0x800000, v124
	s_nop 1
	v_addc_co_u32_e32 v147, vcc, 0, v125, vcc
	global_load_dwordx4 v[164:167], v[146:147], off
	v_add_co_u32_e32 v146, vcc, 0xa00000, v124
	s_nop 1
	v_addc_co_u32_e32 v147, vcc, 0, v125, vcc
	global_load_dwordx4 v[168:171], v[146:147], off
	v_add_co_u32_e32 v146, vcc, 0xc00000, v124
	s_nop 1
	v_addc_co_u32_e32 v147, vcc, 0, v125, vcc
	global_load_dwordx4 v[172:175], v[146:147], off
	v_add_co_u32_e32 v146, vcc, 0xe00000, v124
	s_nop 1
	v_addc_co_u32_e32 v147, vcc, 0, v125, vcc
	global_load_dwordx4 v[176:179], v[146:147], off
	s_waitcnt vmcnt(0)
	v_readlane_b32 s40, v253, 25
	v_readlane_b32 s41, v253, 26
	v_readlane_b32 s42, v253, 27
	v_readlane_b32 s43, v253, 28
	v_readlane_b32 s44, v253, 29
	v_readlane_b32 s45, v253, 30
	v_readlane_b32 s46, v253, 31
	v_readlane_b32 s47, v253, 32
	v_readlane_b32 s48, v253, 33
	v_readlane_b32 s49, v253, 34
	v_readlane_b32 s50, v253, 35
	v_readlane_b32 s51, v253, 36
	v_pk_fma_f32 v[92:93], v[88:89], s[6:7], v[148:149] op_sel_hi:[1,0,1]
	v_pk_fma_f32 v[94:95], v[90:91], s[6:7], v[150:151] op_sel_hi:[1,0,1]
	v_pk_add_f32 v[92:93], v[92:93], v[152:153]
	v_pk_add_f32 v[94:95], v[94:95], v[154:155]
	v_pk_add_f32 v[92:93], v[92:93], v[156:157]
	v_pk_add_f32 v[94:95], v[94:95], v[158:159]
	v_pk_add_f32 v[92:93], v[92:93], v[160:161]
	v_pk_add_f32 v[94:95], v[94:95], v[162:163]
	v_pk_add_f32 v[92:93], v[92:93], v[164:165]
	v_pk_add_f32 v[94:95], v[94:95], v[166:167]
	v_pk_add_f32 v[92:93], v[92:93], v[168:169]
	v_pk_add_f32 v[94:95], v[94:95], v[170:171]
	v_pk_add_f32 v[92:93], v[92:93], v[172:173]
	v_pk_add_f32 v[94:95], v[94:95], v[174:175]
	v_pk_add_f32 v[90:91], v[94:95], v[178:179]
	v_pk_add_f32 v[88:89], v[92:93], v[176:177]
	s_andn2_saveexec_b64 s[12:13], s[12:13]
	s_cbranch_execz .LBB0_1563
	s_branch .LBB0_1562

.LBB0_1563:
	s_or_b64 exec, exec, s[12:13]
	s_and_saveexec_b64 s[12:13], s[0:1]
	s_xor_b64 s[0:1], exec, s[12:13]
	s_cbranch_execz .LBB0_1565
	v_readlane_b32 s36, v253, 21
	v_or_b32_e32 v104, 0x1c00, v104
	v_readlane_b32 s38, v253, 23
	v_readlane_b32 s39, v253, 24
	v_lshl_add_u64 v[124:125], s[92:93], 0, v[104:105]
	v_readlane_b32 s37, v253, 22
	v_lshl_add_u64 v[92:93], s[38:39], 0, v[104:105]
	global_load_dwordx4 v[92:95], v[92:93], off
	global_load_dwordx4 v[148:151], v[124:125], off
	v_add_co_u32_e32 v146, vcc, 0x200000, v124
	s_nop 1
	v_addc_co_u32_e32 v147, vcc, 0, v125, vcc
	global_load_dwordx4 v[152:155], v[146:147], off
	v_add_co_u32_e32 v146, vcc, 0x400000, v124
	s_nop 1
	v_addc_co_u32_e32 v147, vcc, 0, v125, vcc
	global_load_dwordx4 v[156:159], v[146:147], off
	v_add_co_u32_e32 v146, vcc, 0x600000, v124
	s_nop 1
	v_addc_co_u32_e32 v147, vcc, 0, v125, vcc
	global_load_dwordx4 v[160:163], v[146:147], off
	v_add_co_u32_e32 v146, vcc, 0x800000, v124
	s_nop 1
	v_addc_co_u32_e32 v147, vcc, 0, v125, vcc
	global_load_dwordx4 v[164:167], v[146:147], off
	v_add_co_u32_e32 v146, vcc, 0xa00000, v124
	s_nop 1
	v_addc_co_u32_e32 v147, vcc, 0, v125, vcc
	global_load_dwordx4 v[168:171], v[146:147], off
	v_add_co_u32_e32 v146, vcc, 0xc00000, v124
	s_nop 1
	v_addc_co_u32_e32 v147, vcc, 0, v125, vcc
	global_load_dwordx4 v[172:175], v[146:147], off
	v_add_co_u32_e32 v146, vcc, 0xe00000, v124
	s_nop 1
	v_addc_co_u32_e32 v147, vcc, 0, v125, vcc
	global_load_dwordx4 v[176:179], v[146:147], off
	s_waitcnt vmcnt(0)
	v_readlane_b32 s40, v253, 25
	v_readlane_b32 s41, v253, 26
	v_readlane_b32 s42, v253, 27
	v_readlane_b32 s43, v253, 28
	v_readlane_b32 s44, v253, 29
	v_readlane_b32 s45, v253, 30
	v_readlane_b32 s46, v253, 31
	v_readlane_b32 s47, v253, 32
	v_readlane_b32 s48, v253, 33
	v_readlane_b32 s49, v253, 34
	v_readlane_b32 s50, v253, 35
	v_readlane_b32 s51, v253, 36
	v_pk_fma_f32 v[104:105], v[92:93], s[6:7], v[148:149] op_sel_hi:[1,0,1]
	v_pk_fma_f32 v[106:107], v[94:95], s[6:7], v[150:151] op_sel_hi:[1,0,1]
	v_pk_add_f32 v[104:105], v[104:105], v[152:153]
	v_pk_add_f32 v[106:107], v[106:107], v[154:155]
	v_pk_add_f32 v[104:105], v[104:105], v[156:157]
	v_pk_add_f32 v[106:107], v[106:107], v[158:159]
	v_pk_add_f32 v[104:105], v[104:105], v[160:161]
	v_pk_add_f32 v[106:107], v[106:107], v[162:163]
	v_pk_add_f32 v[104:105], v[104:105], v[164:165]
	v_pk_add_f32 v[106:107], v[106:107], v[166:167]
	v_pk_add_f32 v[104:105], v[104:105], v[168:169]
	v_pk_add_f32 v[106:107], v[106:107], v[170:171]
	v_pk_add_f32 v[104:105], v[104:105], v[172:173]
	v_pk_add_f32 v[106:107], v[106:107], v[174:175]
	v_pk_add_f32 v[94:95], v[106:107], v[178:179]
	v_pk_add_f32 v[92:93], v[104:105], v[176:177]
	s_andn2_saveexec_b64 s[0:1], s[0:1]
	s_cbranch_execz .LBB0_1534
	s_branch .LBB0_1566

.LBB0_2069:
	v_add_u32_e32 v96, 0xffffe000, v117
	s_movk_i32 s2, 0x1fff
	v_lshlrev_b64 v[104:105], 11, v[96:97]
	v_cmp_lt_i32_e64 s[34:35], s2, v117
	v_or_b32_e32 v104, v104, v98
	s_and_saveexec_b64 s[2:3], s[34:35]
	s_xor_b64 s[2:3], exec, s[2:3]
	s_cbranch_execz .LBB0_2071
	v_lshl_add_u64 v[64:65], v[104:105], 1, s[82:83]
	global_load_dwordx2 v[64:65], v[64:65], off
	v_lshl_add_u64 v[72:73], v[104:105], 2, s[84:85]
	global_load_dwordx4 v[148:151], v[72:73], off
	v_add_co_u32_e32 v146, vcc, 0x200000, v72
	s_nop 1
	v_addc_co_u32_e32 v147, vcc, 0, v73, vcc
	global_load_dwordx4 v[152:155], v[146:147], off
	s_waitcnt vmcnt(0)
	v_lshlrev_b32_e32 v68, 16, v64
	v_and_b32_e32 v69, 0xffff0000, v64
	v_lshlrev_b32_e32 v70, 16, v65
	v_and_b32_e32 v71, 0xffff0000, v65
	v_pk_fma_f32 v[68:69], v[68:69], s[92:93], v[148:149] op_sel_hi:[1,0,1]
	v_pk_fma_f32 v[70:71], v[70:71], s[92:93], v[150:151] op_sel_hi:[1,0,1]
	v_pk_add_f32 v[66:67], v[154:155], v[70:71]
	v_pk_add_f32 v[64:65], v[152:153], v[68:69]
	s_or_saveexec_b64 s[2:3], s[2:3]
	v_lshl_add_u64 v[106:107], s[96:97], 0, v[100:101]
	s_xor_b64 exec, exec, s[2:3]
	s_cbranch_execz .LBB0_2073
	s_branch .LBB0_2072

.LBB0_2073:
	s_or_b64 exec, exec, s[2:3]
	s_and_saveexec_b64 s[2:3], s[34:35]
	s_xor_b64 s[2:3], exec, s[2:3]
	s_cbranch_execz .LBB0_2075
	v_or_b32_e32 v68, 0x100, v104
	v_mov_b32_e32 v69, v105
	v_lshl_add_u64 v[70:71], v[68:69], 1, s[82:83]
	global_load_dwordx2 v[70:71], v[70:71], off
	v_lshl_add_u64 v[76:77], v[68:69], 2, s[84:85]
	global_load_dwordx4 v[148:151], v[76:77], off
	v_add_co_u32_e32 v146, vcc, 0x200000, v76
	s_nop 1
	v_addc_co_u32_e32 v147, vcc, 0, v77, vcc
	global_load_dwordx4 v[152:155], v[146:147], off
	s_waitcnt vmcnt(0)
	v_lshlrev_b32_e32 v72, 16, v70
	v_and_b32_e32 v73, 0xffff0000, v70
	v_lshlrev_b32_e32 v74, 16, v71
	v_and_b32_e32 v75, 0xffff0000, v71
	v_pk_fma_f32 v[72:73], v[72:73], s[92:93], v[148:149] op_sel_hi:[1,0,1]
	v_pk_fma_f32 v[74:75], v[74:75], s[92:93], v[150:151] op_sel_hi:[1,0,1]
	v_pk_add_f32 v[70:71], v[154:155], v[74:75]
	v_pk_add_f32 v[68:69], v[152:153], v[72:73]
	s_andn2_saveexec_b64 s[2:3], s[2:3]
	s_cbranch_execz .LBB0_2077
	s_branch .LBB0_2076

.LBB0_2077:
	s_or_b64 exec, exec, s[2:3]
	s_and_saveexec_b64 s[2:3], s[34:35]
	s_xor_b64 s[2:3], exec, s[2:3]
	s_cbranch_execz .LBB0_2079
	v_or_b32_e32 v72, 0x200, v104
	v_mov_b32_e32 v73, v105
	v_lshl_add_u64 v[74:75], v[72:73], 1, s[82:83]
	global_load_dwordx2 v[74:75], v[74:75], off
	v_lshl_add_u64 v[80:81], v[72:73], 2, s[84:85]
	global_load_dwordx4 v[148:151], v[80:81], off
	v_add_co_u32_e32 v146, vcc, 0x200000, v80
	s_nop 1
	v_addc_co_u32_e32 v147, vcc, 0, v81, vcc
	global_load_dwordx4 v[152:155], v[146:147], off
	s_waitcnt vmcnt(0)
	v_lshlrev_b32_e32 v76, 16, v74
	v_and_b32_e32 v77, 0xffff0000, v74
	v_lshlrev_b32_e32 v78, 16, v75
	v_and_b32_e32 v79, 0xffff0000, v75
	v_pk_fma_f32 v[76:77], v[76:77], s[92:93], v[148:149] op_sel_hi:[1,0,1]
	v_pk_fma_f32 v[78:79], v[78:79], s[92:93], v[150:151] op_sel_hi:[1,0,1]
	v_pk_add_f32 v[74:75], v[154:155], v[78:79]
	v_pk_add_f32 v[72:73], v[152:153], v[76:77]
	s_andn2_saveexec_b64 s[2:3], s[2:3]
	s_cbranch_execz .LBB0_2081
	s_branch .LBB0_2080

.LBB0_2081:
	s_or_b64 exec, exec, s[2:3]
	s_and_saveexec_b64 s[2:3], s[34:35]
	s_xor_b64 s[2:3], exec, s[2:3]
	s_cbranch_execz .LBB0_2083
	v_or_b32_e32 v76, 0x300, v104
	v_mov_b32_e32 v77, v105
	v_lshl_add_u64 v[78:79], v[76:77], 1, s[82:83]
	global_load_dwordx2 v[78:79], v[78:79], off
	v_lshl_add_u64 v[84:85], v[76:77], 2, s[84:85]
	global_load_dwordx4 v[148:151], v[84:85], off
	v_add_co_u32_e32 v146, vcc, 0x200000, v84
	s_nop 1
	v_addc_co_u32_e32 v147, vcc, 0, v85, vcc
	global_load_dwordx4 v[152:155], v[146:147], off
	s_waitcnt vmcnt(0)
	v_lshlrev_b32_e32 v80, 16, v78
	v_and_b32_e32 v81, 0xffff0000, v78
	v_lshlrev_b32_e32 v82, 16, v79
	v_and_b32_e32 v83, 0xffff0000, v79
	v_pk_fma_f32 v[80:81], v[80:81], s[92:93], v[148:149] op_sel_hi:[1,0,1]
	v_pk_fma_f32 v[82:83], v[82:83], s[92:93], v[150:151] op_sel_hi:[1,0,1]
	v_pk_add_f32 v[78:79], v[154:155], v[82:83]
	v_pk_add_f32 v[76:77], v[152:153], v[80:81]
	s_andn2_saveexec_b64 s[2:3], s[2:3]
	s_cbranch_execz .LBB0_2085
	s_branch .LBB0_2084

.LBB0_2085:
	s_or_b64 exec, exec, s[2:3]
	s_and_saveexec_b64 s[2:3], s[34:35]
	s_xor_b64 s[2:3], exec, s[2:3]
	s_cbranch_execz .LBB0_2087
	v_or_b32_e32 v80, 0x400, v104
	v_mov_b32_e32 v81, v105
	v_lshl_add_u64 v[82:83], v[80:81], 1, s[82:83]
	global_load_dwordx2 v[82:83], v[82:83], off
	v_lshl_add_u64 v[88:89], v[80:81], 2, s[84:85]
	global_load_dwordx4 v[148:151], v[88:89], off
	v_add_co_u32_e32 v146, vcc, 0x200000, v88
	s_nop 1
	v_addc_co_u32_e32 v147, vcc, 0, v89, vcc
	global_load_dwordx4 v[152:155], v[146:147], off
	s_waitcnt vmcnt(0)
	v_lshlrev_b32_e32 v84, 16, v82
	v_and_b32_e32 v85, 0xffff0000, v82
	v_lshlrev_b32_e32 v86, 16, v83
	v_and_b32_e32 v87, 0xffff0000, v83
	v_pk_fma_f32 v[84:85], v[84:85], s[92:93], v[148:149] op_sel_hi:[1,0,1]
	v_pk_fma_f32 v[86:87], v[86:87], s[92:93], v[150:151] op_sel_hi:[1,0,1]
	v_pk_add_f32 v[82:83], v[154:155], v[86:87]
	v_pk_add_f32 v[80:81], v[152:153], v[84:85]
	s_andn2_saveexec_b64 s[2:3], s[2:3]
	s_cbranch_execz .LBB0_2089
	s_branch .LBB0_2088

.LBB0_2089:
	s_or_b64 exec, exec, s[2:3]
	s_and_saveexec_b64 s[2:3], s[34:35]
	s_xor_b64 s[2:3], exec, s[2:3]
	s_cbranch_execz .LBB0_2091
	v_or_b32_e32 v84, 0x500, v104
	v_mov_b32_e32 v85, v105
	v_lshl_add_u64 v[86:87], v[84:85], 1, s[82:83]
	global_load_dwordx2 v[86:87], v[86:87], off
	v_lshl_add_u64 v[92:93], v[84:85], 2, s[84:85]
	global_load_dwordx4 v[148:151], v[92:93], off
	v_add_co_u32_e32 v146, vcc, 0x200000, v92
	s_nop 1
	v_addc_co_u32_e32 v147, vcc, 0, v93, vcc
	global_load_dwordx4 v[152:155], v[146:147], off
	s_waitcnt vmcnt(0)
	v_lshlrev_b32_e32 v88, 16, v86
	v_and_b32_e32 v89, 0xffff0000, v86
	v_lshlrev_b32_e32 v90, 16, v87
	v_and_b32_e32 v91, 0xffff0000, v87
	v_pk_fma_f32 v[88:89], v[88:89], s[92:93], v[148:149] op_sel_hi:[1,0,1]
	v_pk_fma_f32 v[90:91], v[90:91], s[92:93], v[150:151] op_sel_hi:[1,0,1]
	v_pk_add_f32 v[86:87], v[154:155], v[90:91]
	v_pk_add_f32 v[84:85], v[152:153], v[88:89]
	s_andn2_saveexec_b64 s[2:3], s[2:3]
	s_cbranch_execz .LBB0_2093
	s_branch .LBB0_2092

.LBB0_2093:
	s_or_b64 exec, exec, s[2:3]
	s_and_saveexec_b64 s[2:3], s[34:35]
	s_xor_b64 s[2:3], exec, s[2:3]
	s_cbranch_execz .LBB0_2095
	v_or_b32_e32 v88, 0x600, v104
	v_mov_b32_e32 v89, v105
	v_lshl_add_u64 v[90:91], v[88:89], 1, s[82:83]
	global_load_dwordx2 v[90:91], v[90:91], off
	v_lshl_add_u64 v[124:125], v[88:89], 2, s[84:85]
	global_load_dwordx4 v[148:151], v[124:125], off
	v_add_co_u32_e32 v146, vcc, 0x200000, v124
	s_nop 1
	v_addc_co_u32_e32 v147, vcc, 0, v125, vcc
	global_load_dwordx4 v[152:155], v[146:147], off
	s_waitcnt vmcnt(0)
	v_lshlrev_b32_e32 v92, 16, v90
	v_and_b32_e32 v93, 0xffff0000, v90
	v_lshlrev_b32_e32 v94, 16, v91
	v_and_b32_e32 v95, 0xffff0000, v91
	v_pk_fma_f32 v[92:93], v[92:93], s[92:93], v[148:149] op_sel_hi:[1,0,1]
	v_pk_fma_f32 v[94:95], v[94:95], s[92:93], v[150:151] op_sel_hi:[1,0,1]
	v_pk_add_f32 v[90:91], v[154:155], v[94:95]
	v_pk_add_f32 v[88:89], v[152:153], v[92:93]
	s_andn2_saveexec_b64 s[2:3], s[2:3]
	s_cbranch_execz .LBB0_2097
	s_branch .LBB0_2096

.LBB0_2097:
	s_or_b64 exec, exec, s[2:3]
	s_and_saveexec_b64 s[2:3], s[34:35]
	s_xor_b64 s[34:35], exec, s[2:3]
	s_cbranch_execz .LBB0_2099
	v_or_b32_e32 v104, 0x700, v104
	v_lshl_add_u64 v[92:93], v[104:105], 1, s[82:83]
	global_load_dwordx2 v[92:93], v[92:93], off
	v_lshl_add_u64 v[104:105], v[104:105], 2, s[84:85]
	global_load_dwordx4 v[148:151], v[104:105], off
	v_add_co_u32_e32 v146, vcc, 0x200000, v104
	s_nop 1
	v_addc_co_u32_e32 v147, vcc, 0, v105, vcc
	global_load_dwordx4 v[152:155], v[146:147], off
	s_waitcnt vmcnt(0)
	v_lshlrev_b32_e32 v106, 16, v92
	v_and_b32_e32 v107, 0xffff0000, v92
	v_lshlrev_b32_e32 v124, 16, v93
	v_and_b32_e32 v125, 0xffff0000, v93
	v_pk_fma_f32 v[106:107], v[106:107], s[92:93], v[148:149] op_sel_hi:[1,0,1]
	v_pk_fma_f32 v[124:125], v[124:125], s[92:93], v[150:151] op_sel_hi:[1,0,1]
	v_pk_add_f32 v[94:95], v[154:155], v[124:125]
	v_pk_add_f32 v[92:93], v[152:153], v[106:107]
	s_andn2_saveexec_b64 s[2:3], s[34:35]
	s_cbranch_execz .LBB0_2068
	s_branch .LBB0_2100

.LBB0_2489:
	v_add_u32_e32 v96, 0xffffe000, v123
	s_movk_i32 s0, 0x1fff
	v_lshlrev_b64 v[106:107], 11, v[96:97]
	v_cmp_lt_i32_e64 s[0:1], s0, v123
	v_or_b32_e32 v106, v106, v98
	s_and_saveexec_b64 s[4:5], s[0:1]
	s_xor_b64 s[4:5], exec, s[4:5]
	s_cbranch_execz .LBB0_2491
	v_lshl_add_u64 v[64:65], v[106:107], 1, s[82:83]
	global_load_dwordx2 v[64:65], v[64:65], off
	v_lshl_add_u64 v[72:73], v[106:107], 2, s[84:85]
	global_load_dwordx4 v[148:151], v[72:73], off
	v_add_co_u32_e32 v146, vcc, s12, v72
	s_nop 1
	v_addc_co_u32_e32 v147, vcc, 0, v73, vcc
	global_load_dwordx4 v[152:155], v[146:147], off
	v_add_co_u32_e32 v146, vcc, s13, v72
	s_nop 1
	v_addc_co_u32_e32 v147, vcc, 0, v73, vcc
	global_load_dwordx4 v[156:159], v[146:147], off
	v_add_co_u32_e32 v146, vcc, s14, v72
	s_nop 1
	v_addc_co_u32_e32 v147, vcc, 0, v73, vcc
	global_load_dwordx4 v[160:163], v[146:147], off
	v_add_co_u32_e32 v146, vcc, s15, v72
	s_nop 1
	v_addc_co_u32_e32 v147, vcc, 0, v73, vcc
	global_load_dwordx4 v[164:167], v[146:147], off
	v_add_co_u32_e32 v146, vcc, s16, v72
	s_nop 1
	v_addc_co_u32_e32 v147, vcc, 0, v73, vcc
	global_load_dwordx4 v[168:171], v[146:147], off
	v_add_co_u32_e32 v146, vcc, s17, v72
	s_nop 1
	v_addc_co_u32_e32 v147, vcc, 0, v73, vcc
	global_load_dwordx4 v[172:175], v[146:147], off
	v_add_co_u32_e32 v146, vcc, s18, v72
	s_nop 1
	v_addc_co_u32_e32 v147, vcc, 0, v73, vcc
	global_load_dwordx4 v[176:179], v[146:147], off
	v_add_co_u32_e32 v146, vcc, s19, v72
	s_nop 1
	v_addc_co_u32_e32 v147, vcc, 0, v73, vcc
	global_load_dwordx4 v[180:183], v[146:147], off
	v_add_co_u32_e32 v146, vcc, s20, v72
	s_nop 1
	v_addc_co_u32_e32 v147, vcc, 0, v73, vcc
	global_load_dwordx4 v[184:187], v[146:147], off
	v_add_co_u32_e32 v146, vcc, 0x1400000, v72
	s_nop 1
	v_addc_co_u32_e32 v147, vcc, 0, v73, vcc
	global_load_dwordx4 v[188:191], v[146:147], off
	s_waitcnt vmcnt(0)
	v_lshlrev_b32_e32 v68, 16, v64
	v_and_b32_e32 v69, 0xffff0000, v64
	v_lshlrev_b32_e32 v70, 16, v65
	v_and_b32_e32 v71, 0xffff0000, v65
	v_pk_fma_f32 v[68:69], v[68:69], s[92:93], v[148:149] op_sel_hi:[1,0,1]
	v_pk_fma_f32 v[70:71], v[70:71], s[92:93], v[150:151] op_sel_hi:[1,0,1]
	v_pk_add_f32 v[68:69], v[152:153], v[68:69]
	v_pk_add_f32 v[70:71], v[154:155], v[70:71]
	v_pk_add_f32 v[68:69], v[156:157], v[68:69]
	v_pk_add_f32 v[70:71], v[158:159], v[70:71]
	v_pk_add_f32 v[68:69], v[160:161], v[68:69]
	v_pk_add_f32 v[70:71], v[162:163], v[70:71]
	v_pk_add_f32 v[68:69], v[164:165], v[68:69]
	v_pk_add_f32 v[70:71], v[166:167], v[70:71]
	v_pk_add_f32 v[68:69], v[168:169], v[68:69]
	v_pk_add_f32 v[70:71], v[170:171], v[70:71]
	v_pk_add_f32 v[68:69], v[172:173], v[68:69]
	v_pk_add_f32 v[70:71], v[174:175], v[70:71]
	v_pk_add_f32 v[68:69], v[176:177], v[68:69]
	v_pk_add_f32 v[70:71], v[178:179], v[70:71]
	v_pk_add_f32 v[68:69], v[180:181], v[68:69]
	v_pk_add_f32 v[70:71], v[182:183], v[70:71]
	v_pk_add_f32 v[68:69], v[184:185], v[68:69]
	v_pk_add_f32 v[70:71], v[186:187], v[70:71]
	v_pk_add_f32 v[66:67], v[190:191], v[70:71]
	v_pk_add_f32 v[64:65], v[188:189], v[68:69]
	s_or_saveexec_b64 s[4:5], s[4:5]
	v_lshl_add_u64 v[108:109], v[102:103], 0, v[100:101]
	s_xor_b64 exec, exec, s[4:5]
	s_cbranch_execz .LBB0_2493
	s_branch .LBB0_2492

.LBB0_2493:
	s_or_b64 exec, exec, s[4:5]
	s_and_saveexec_b64 s[4:5], s[0:1]
	s_xor_b64 s[4:5], exec, s[4:5]
	s_cbranch_execz .LBB0_2495
	v_or_b32_e32 v68, 0x100, v106
	v_mov_b32_e32 v69, v107
	v_lshl_add_u64 v[70:71], v[68:69], 1, s[82:83]
	global_load_dwordx2 v[70:71], v[70:71], off
	v_lshl_add_u64 v[76:77], v[68:69], 2, s[84:85]
	global_load_dwordx4 v[148:151], v[76:77], off
	v_add_co_u32_e32 v146, vcc, s12, v76
	s_nop 1
	v_addc_co_u32_e32 v147, vcc, 0, v77, vcc
	global_load_dwordx4 v[152:155], v[146:147], off
	v_add_co_u32_e32 v146, vcc, s13, v76
	s_nop 1
	v_addc_co_u32_e32 v147, vcc, 0, v77, vcc
	global_load_dwordx4 v[156:159], v[146:147], off
	v_add_co_u32_e32 v146, vcc, s14, v76
	s_nop 1
	v_addc_co_u32_e32 v147, vcc, 0, v77, vcc
	global_load_dwordx4 v[160:163], v[146:147], off
	v_add_co_u32_e32 v146, vcc, s15, v76
	s_nop 1
	v_addc_co_u32_e32 v147, vcc, 0, v77, vcc
	global_load_dwordx4 v[164:167], v[146:147], off
	v_add_co_u32_e32 v146, vcc, s16, v76
	s_nop 1
	v_addc_co_u32_e32 v147, vcc, 0, v77, vcc
	global_load_dwordx4 v[168:171], v[146:147], off
	v_add_co_u32_e32 v146, vcc, s17, v76
	s_nop 1
	v_addc_co_u32_e32 v147, vcc, 0, v77, vcc
	global_load_dwordx4 v[172:175], v[146:147], off
	v_add_co_u32_e32 v146, vcc, s18, v76
	s_nop 1
	v_addc_co_u32_e32 v147, vcc, 0, v77, vcc
	global_load_dwordx4 v[176:179], v[146:147], off
	v_add_co_u32_e32 v146, vcc, s19, v76
	s_nop 1
	v_addc_co_u32_e32 v147, vcc, 0, v77, vcc
	global_load_dwordx4 v[180:183], v[146:147], off
	v_add_co_u32_e32 v146, vcc, s20, v76
	s_nop 1
	v_addc_co_u32_e32 v147, vcc, 0, v77, vcc
	global_load_dwordx4 v[184:187], v[146:147], off
	v_add_co_u32_e32 v146, vcc, 0x1400000, v76
	s_nop 1
	v_addc_co_u32_e32 v147, vcc, 0, v77, vcc
	global_load_dwordx4 v[188:191], v[146:147], off
	s_waitcnt vmcnt(0)
	v_lshlrev_b32_e32 v72, 16, v70
	v_and_b32_e32 v73, 0xffff0000, v70
	v_lshlrev_b32_e32 v74, 16, v71
	v_and_b32_e32 v75, 0xffff0000, v71
	v_pk_fma_f32 v[72:73], v[72:73], s[92:93], v[148:149] op_sel_hi:[1,0,1]
	v_pk_fma_f32 v[74:75], v[74:75], s[92:93], v[150:151] op_sel_hi:[1,0,1]
	v_pk_add_f32 v[72:73], v[152:153], v[72:73]
	v_pk_add_f32 v[74:75], v[154:155], v[74:75]
	v_pk_add_f32 v[72:73], v[156:157], v[72:73]
	v_pk_add_f32 v[74:75], v[158:159], v[74:75]
	v_pk_add_f32 v[72:73], v[160:161], v[72:73]
	v_pk_add_f32 v[74:75], v[162:163], v[74:75]
	v_pk_add_f32 v[72:73], v[164:165], v[72:73]
	v_pk_add_f32 v[74:75], v[166:167], v[74:75]
	v_pk_add_f32 v[72:73], v[168:169], v[72:73]
	v_pk_add_f32 v[74:75], v[170:171], v[74:75]
	v_pk_add_f32 v[72:73], v[172:173], v[72:73]
	v_pk_add_f32 v[74:75], v[174:175], v[74:75]
	v_pk_add_f32 v[72:73], v[176:177], v[72:73]
	v_pk_add_f32 v[74:75], v[178:179], v[74:75]
	v_pk_add_f32 v[72:73], v[180:181], v[72:73]
	v_pk_add_f32 v[74:75], v[182:183], v[74:75]
	v_pk_add_f32 v[72:73], v[184:185], v[72:73]
	v_pk_add_f32 v[74:75], v[186:187], v[74:75]
	v_pk_add_f32 v[70:71], v[190:191], v[74:75]
	v_pk_add_f32 v[68:69], v[188:189], v[72:73]
	s_andn2_saveexec_b64 s[4:5], s[4:5]
	s_cbranch_execz .LBB0_2497
	s_branch .LBB0_2496

.LBB0_2497:
	s_or_b64 exec, exec, s[4:5]
	s_and_saveexec_b64 s[4:5], s[0:1]
	s_xor_b64 s[4:5], exec, s[4:5]
	s_cbranch_execz .LBB0_2499
	v_or_b32_e32 v72, 0x200, v106
	v_mov_b32_e32 v73, v107
	v_lshl_add_u64 v[74:75], v[72:73], 1, s[82:83]
	global_load_dwordx2 v[74:75], v[74:75], off
	v_lshl_add_u64 v[80:81], v[72:73], 2, s[84:85]
	global_load_dwordx4 v[148:151], v[80:81], off
	v_add_co_u32_e32 v146, vcc, s12, v80
	s_nop 1
	v_addc_co_u32_e32 v147, vcc, 0, v81, vcc
	global_load_dwordx4 v[152:155], v[146:147], off
	v_add_co_u32_e32 v146, vcc, s13, v80
	s_nop 1
	v_addc_co_u32_e32 v147, vcc, 0, v81, vcc
	global_load_dwordx4 v[156:159], v[146:147], off
	v_add_co_u32_e32 v146, vcc, s14, v80
	s_nop 1
	v_addc_co_u32_e32 v147, vcc, 0, v81, vcc
	global_load_dwordx4 v[160:163], v[146:147], off
	v_add_co_u32_e32 v146, vcc, s15, v80
	s_nop 1
	v_addc_co_u32_e32 v147, vcc, 0, v81, vcc
	global_load_dwordx4 v[164:167], v[146:147], off
	v_add_co_u32_e32 v146, vcc, s16, v80
	s_nop 1
	v_addc_co_u32_e32 v147, vcc, 0, v81, vcc
	global_load_dwordx4 v[168:171], v[146:147], off
	v_add_co_u32_e32 v146, vcc, s17, v80
	s_nop 1
	v_addc_co_u32_e32 v147, vcc, 0, v81, vcc
	global_load_dwordx4 v[172:175], v[146:147], off
	v_add_co_u32_e32 v146, vcc, s18, v80
	s_nop 1
	v_addc_co_u32_e32 v147, vcc, 0, v81, vcc
	global_load_dwordx4 v[176:179], v[146:147], off
	v_add_co_u32_e32 v146, vcc, s19, v80
	s_nop 1
	v_addc_co_u32_e32 v147, vcc, 0, v81, vcc
	global_load_dwordx4 v[180:183], v[146:147], off
	v_add_co_u32_e32 v146, vcc, s20, v80
	s_nop 1
	v_addc_co_u32_e32 v147, vcc, 0, v81, vcc
	global_load_dwordx4 v[184:187], v[146:147], off
	v_add_co_u32_e32 v146, vcc, 0x1400000, v80
	s_nop 1
	v_addc_co_u32_e32 v147, vcc, 0, v81, vcc
	global_load_dwordx4 v[188:191], v[146:147], off
	s_waitcnt vmcnt(0)
	v_lshlrev_b32_e32 v76, 16, v74
	v_and_b32_e32 v77, 0xffff0000, v74
	v_lshlrev_b32_e32 v78, 16, v75
	v_and_b32_e32 v79, 0xffff0000, v75
	v_pk_fma_f32 v[76:77], v[76:77], s[92:93], v[148:149] op_sel_hi:[1,0,1]
	v_pk_fma_f32 v[78:79], v[78:79], s[92:93], v[150:151] op_sel_hi:[1,0,1]
	v_pk_add_f32 v[76:77], v[152:153], v[76:77]
	v_pk_add_f32 v[78:79], v[154:155], v[78:79]
	v_pk_add_f32 v[76:77], v[156:157], v[76:77]
	v_pk_add_f32 v[78:79], v[158:159], v[78:79]
	v_pk_add_f32 v[76:77], v[160:161], v[76:77]
	v_pk_add_f32 v[78:79], v[162:163], v[78:79]
	v_pk_add_f32 v[76:77], v[164:165], v[76:77]
	v_pk_add_f32 v[78:79], v[166:167], v[78:79]
	v_pk_add_f32 v[76:77], v[168:169], v[76:77]
	v_pk_add_f32 v[78:79], v[170:171], v[78:79]
	v_pk_add_f32 v[76:77], v[172:173], v[76:77]
	v_pk_add_f32 v[78:79], v[174:175], v[78:79]
	v_pk_add_f32 v[76:77], v[176:177], v[76:77]
	v_pk_add_f32 v[78:79], v[178:179], v[78:79]
	v_pk_add_f32 v[76:77], v[180:181], v[76:77]
	v_pk_add_f32 v[78:79], v[182:183], v[78:79]
	v_pk_add_f32 v[76:77], v[184:185], v[76:77]
	v_pk_add_f32 v[78:79], v[186:187], v[78:79]
	v_pk_add_f32 v[74:75], v[190:191], v[78:79]
	v_pk_add_f32 v[72:73], v[188:189], v[76:77]
	s_andn2_saveexec_b64 s[4:5], s[4:5]
	s_cbranch_execz .LBB0_2501
	s_branch .LBB0_2500

.LBB0_2501:
	s_or_b64 exec, exec, s[4:5]
	s_and_saveexec_b64 s[4:5], s[0:1]
	s_xor_b64 s[4:5], exec, s[4:5]
	s_cbranch_execz .LBB0_2503
	v_or_b32_e32 v76, 0x300, v106
	v_mov_b32_e32 v77, v107
	v_lshl_add_u64 v[78:79], v[76:77], 1, s[82:83]
	global_load_dwordx2 v[78:79], v[78:79], off
	v_lshl_add_u64 v[84:85], v[76:77], 2, s[84:85]
	global_load_dwordx4 v[148:151], v[84:85], off
	v_add_co_u32_e32 v146, vcc, s12, v84
	s_nop 1
	v_addc_co_u32_e32 v147, vcc, 0, v85, vcc
	global_load_dwordx4 v[152:155], v[146:147], off
	v_add_co_u32_e32 v146, vcc, s13, v84
	s_nop 1
	v_addc_co_u32_e32 v147, vcc, 0, v85, vcc
	global_load_dwordx4 v[156:159], v[146:147], off
	v_add_co_u32_e32 v146, vcc, s14, v84
	s_nop 1
	v_addc_co_u32_e32 v147, vcc, 0, v85, vcc
	global_load_dwordx4 v[160:163], v[146:147], off
	v_add_co_u32_e32 v146, vcc, s15, v84
	s_nop 1
	v_addc_co_u32_e32 v147, vcc, 0, v85, vcc
	global_load_dwordx4 v[164:167], v[146:147], off
	v_add_co_u32_e32 v146, vcc, s16, v84
	s_nop 1
	v_addc_co_u32_e32 v147, vcc, 0, v85, vcc
	global_load_dwordx4 v[168:171], v[146:147], off
	v_add_co_u32_e32 v146, vcc, s17, v84
	s_nop 1
	v_addc_co_u32_e32 v147, vcc, 0, v85, vcc
	global_load_dwordx4 v[172:175], v[146:147], off
	v_add_co_u32_e32 v146, vcc, s18, v84
	s_nop 1
	v_addc_co_u32_e32 v147, vcc, 0, v85, vcc
	global_load_dwordx4 v[176:179], v[146:147], off
	v_add_co_u32_e32 v146, vcc, s19, v84
	s_nop 1
	v_addc_co_u32_e32 v147, vcc, 0, v85, vcc
	global_load_dwordx4 v[180:183], v[146:147], off
	v_add_co_u32_e32 v146, vcc, s20, v84
	s_nop 1
	v_addc_co_u32_e32 v147, vcc, 0, v85, vcc
	global_load_dwordx4 v[184:187], v[146:147], off
	v_add_co_u32_e32 v146, vcc, 0x1400000, v84
	s_nop 1
	v_addc_co_u32_e32 v147, vcc, 0, v85, vcc
	global_load_dwordx4 v[188:191], v[146:147], off
	s_waitcnt vmcnt(0)
	v_lshlrev_b32_e32 v80, 16, v78
	v_and_b32_e32 v81, 0xffff0000, v78
	v_lshlrev_b32_e32 v82, 16, v79
	s_waitcnt lgkmcnt(0)
	v_and_b32_e32 v83, 0xffff0000, v79
	v_pk_fma_f32 v[80:81], v[80:81], s[92:93], v[148:149] op_sel_hi:[1,0,1]
	v_pk_fma_f32 v[82:83], v[82:83], s[92:93], v[150:151] op_sel_hi:[1,0,1]
	v_pk_add_f32 v[80:81], v[152:153], v[80:81]
	v_pk_add_f32 v[82:83], v[154:155], v[82:83]
	v_pk_add_f32 v[80:81], v[156:157], v[80:81]
	v_pk_add_f32 v[82:83], v[158:159], v[82:83]
	v_pk_add_f32 v[80:81], v[160:161], v[80:81]
	v_pk_add_f32 v[82:83], v[162:163], v[82:83]
	v_pk_add_f32 v[80:81], v[164:165], v[80:81]
	v_pk_add_f32 v[82:83], v[166:167], v[82:83]
	v_pk_add_f32 v[80:81], v[168:169], v[80:81]
	v_pk_add_f32 v[82:83], v[170:171], v[82:83]
	v_pk_add_f32 v[80:81], v[172:173], v[80:81]
	v_pk_add_f32 v[82:83], v[174:175], v[82:83]
	v_pk_add_f32 v[80:81], v[176:177], v[80:81]
	v_pk_add_f32 v[82:83], v[178:179], v[82:83]
	v_pk_add_f32 v[80:81], v[180:181], v[80:81]
	v_pk_add_f32 v[82:83], v[182:183], v[82:83]
	v_pk_add_f32 v[80:81], v[184:185], v[80:81]
	v_pk_add_f32 v[82:83], v[186:187], v[82:83]
	v_pk_add_f32 v[78:79], v[190:191], v[82:83]
	v_pk_add_f32 v[76:77], v[188:189], v[80:81]
	s_andn2_saveexec_b64 s[4:5], s[4:5]
	s_cbranch_execz .LBB0_2505
	s_branch .LBB0_2504

.LBB0_2505:
	s_or_b64 exec, exec, s[4:5]
	s_and_saveexec_b64 s[4:5], s[0:1]
	s_xor_b64 s[4:5], exec, s[4:5]
	s_cbranch_execz .LBB0_2507
	v_or_b32_e32 v80, 0x400, v106
	v_mov_b32_e32 v81, v107
	s_waitcnt lgkmcnt(0)
	v_lshl_add_u64 v[82:83], v[80:81], 1, s[82:83]
	global_load_dwordx2 v[82:83], v[82:83], off
	v_lshl_add_u64 v[88:89], v[80:81], 2, s[84:85]
	global_load_dwordx4 v[148:151], v[88:89], off
	v_add_co_u32_e32 v146, vcc, s12, v88
	s_nop 1
	v_addc_co_u32_e32 v147, vcc, 0, v89, vcc
	global_load_dwordx4 v[152:155], v[146:147], off
	v_add_co_u32_e32 v146, vcc, s13, v88
	s_nop 1
	v_addc_co_u32_e32 v147, vcc, 0, v89, vcc
	global_load_dwordx4 v[156:159], v[146:147], off
	v_add_co_u32_e32 v146, vcc, s14, v88
	s_nop 1
	v_addc_co_u32_e32 v147, vcc, 0, v89, vcc
	global_load_dwordx4 v[160:163], v[146:147], off
	v_add_co_u32_e32 v146, vcc, s15, v88
	s_nop 1
	v_addc_co_u32_e32 v147, vcc, 0, v89, vcc
	global_load_dwordx4 v[164:167], v[146:147], off
	v_add_co_u32_e32 v146, vcc, s16, v88
	s_nop 1
	v_addc_co_u32_e32 v147, vcc, 0, v89, vcc
	global_load_dwordx4 v[168:171], v[146:147], off
	v_add_co_u32_e32 v146, vcc, s17, v88
	s_nop 1
	v_addc_co_u32_e32 v147, vcc, 0, v89, vcc
	global_load_dwordx4 v[172:175], v[146:147], off
	v_add_co_u32_e32 v146, vcc, s18, v88
	s_nop 1
	v_addc_co_u32_e32 v147, vcc, 0, v89, vcc
	global_load_dwordx4 v[176:179], v[146:147], off
	v_add_co_u32_e32 v146, vcc, s19, v88
	s_nop 1
	v_addc_co_u32_e32 v147, vcc, 0, v89, vcc
	global_load_dwordx4 v[180:183], v[146:147], off
	v_add_co_u32_e32 v146, vcc, s20, v88
	s_nop 1
	v_addc_co_u32_e32 v147, vcc, 0, v89, vcc
	global_load_dwordx4 v[184:187], v[146:147], off
	v_add_co_u32_e32 v146, vcc, 0x1400000, v88
	s_nop 1
	v_addc_co_u32_e32 v147, vcc, 0, v89, vcc
	global_load_dwordx4 v[188:191], v[146:147], off
	s_waitcnt vmcnt(0)
	v_lshlrev_b32_e32 v84, 16, v82
	v_and_b32_e32 v85, 0xffff0000, v82
	v_lshlrev_b32_e32 v86, 16, v83
	v_and_b32_e32 v87, 0xffff0000, v83
	v_pk_fma_f32 v[84:85], v[84:85], s[92:93], v[148:149] op_sel_hi:[1,0,1]
	v_pk_fma_f32 v[86:87], v[86:87], s[92:93], v[150:151] op_sel_hi:[1,0,1]
	v_pk_add_f32 v[84:85], v[152:153], v[84:85]
	v_pk_add_f32 v[86:87], v[154:155], v[86:87]
	v_pk_add_f32 v[84:85], v[156:157], v[84:85]
	v_pk_add_f32 v[86:87], v[158:159], v[86:87]
	v_pk_add_f32 v[84:85], v[160:161], v[84:85]
	v_pk_add_f32 v[86:87], v[162:163], v[86:87]
	v_pk_add_f32 v[84:85], v[164:165], v[84:85]
	v_pk_add_f32 v[86:87], v[166:167], v[86:87]
	v_pk_add_f32 v[84:85], v[168:169], v[84:85]
	v_pk_add_f32 v[86:87], v[170:171], v[86:87]
	v_pk_add_f32 v[84:85], v[172:173], v[84:85]
	v_pk_add_f32 v[86:87], v[174:175], v[86:87]
	v_pk_add_f32 v[84:85], v[176:177], v[84:85]
	v_pk_add_f32 v[86:87], v[178:179], v[86:87]
	v_pk_add_f32 v[84:85], v[180:181], v[84:85]
	v_pk_add_f32 v[86:87], v[182:183], v[86:87]
	v_pk_add_f32 v[84:85], v[184:185], v[84:85]
	v_pk_add_f32 v[86:87], v[186:187], v[86:87]
	v_pk_add_f32 v[82:83], v[190:191], v[86:87]
	v_pk_add_f32 v[80:81], v[188:189], v[84:85]
	s_andn2_saveexec_b64 s[4:5], s[4:5]
	s_cbranch_execz .LBB0_2509
	s_branch .LBB0_2508

.LBB0_2509:
	s_or_b64 exec, exec, s[4:5]
	s_and_saveexec_b64 s[4:5], s[0:1]
	s_xor_b64 s[4:5], exec, s[4:5]
	s_cbranch_execz .LBB0_2511
	v_or_b32_e32 v84, 0x500, v106
	v_mov_b32_e32 v85, v107
	v_lshl_add_u64 v[86:87], v[84:85], 1, s[82:83]
	global_load_dwordx2 v[86:87], v[86:87], off
	v_lshl_add_u64 v[92:93], v[84:85], 2, s[84:85]
	global_load_dwordx4 v[148:151], v[92:93], off
	v_add_co_u32_e32 v146, vcc, s12, v92
	s_nop 1
	v_addc_co_u32_e32 v147, vcc, 0, v93, vcc
	global_load_dwordx4 v[152:155], v[146:147], off
	v_add_co_u32_e32 v146, vcc, s13, v92
	s_nop 1
	v_addc_co_u32_e32 v147, vcc, 0, v93, vcc
	global_load_dwordx4 v[156:159], v[146:147], off
	v_add_co_u32_e32 v146, vcc, s14, v92
	s_nop 1
	v_addc_co_u32_e32 v147, vcc, 0, v93, vcc
	global_load_dwordx4 v[160:163], v[146:147], off
	v_add_co_u32_e32 v146, vcc, s15, v92
	s_nop 1
	v_addc_co_u32_e32 v147, vcc, 0, v93, vcc
	global_load_dwordx4 v[164:167], v[146:147], off
	v_add_co_u32_e32 v146, vcc, s16, v92
	s_nop 1
	v_addc_co_u32_e32 v147, vcc, 0, v93, vcc
	global_load_dwordx4 v[168:171], v[146:147], off
	v_add_co_u32_e32 v146, vcc, s17, v92
	s_nop 1
	v_addc_co_u32_e32 v147, vcc, 0, v93, vcc
	global_load_dwordx4 v[172:175], v[146:147], off
	v_add_co_u32_e32 v146, vcc, s18, v92
	s_nop 1
	v_addc_co_u32_e32 v147, vcc, 0, v93, vcc
	global_load_dwordx4 v[176:179], v[146:147], off
	v_add_co_u32_e32 v146, vcc, s19, v92
	s_nop 1
	v_addc_co_u32_e32 v147, vcc, 0, v93, vcc
	global_load_dwordx4 v[180:183], v[146:147], off
	v_add_co_u32_e32 v146, vcc, s20, v92
	s_nop 1
	v_addc_co_u32_e32 v147, vcc, 0, v93, vcc
	global_load_dwordx4 v[184:187], v[146:147], off
	v_add_co_u32_e32 v146, vcc, 0x1400000, v92
	s_nop 1
	v_addc_co_u32_e32 v147, vcc, 0, v93, vcc
	global_load_dwordx4 v[188:191], v[146:147], off
	s_waitcnt vmcnt(0)
	v_lshlrev_b32_e32 v88, 16, v86
	v_and_b32_e32 v89, 0xffff0000, v86
	v_lshlrev_b32_e32 v90, 16, v87
	v_and_b32_e32 v91, 0xffff0000, v87
	v_pk_fma_f32 v[88:89], v[88:89], s[92:93], v[148:149] op_sel_hi:[1,0,1]
	v_pk_fma_f32 v[90:91], v[90:91], s[92:93], v[150:151] op_sel_hi:[1,0,1]
	v_pk_add_f32 v[88:89], v[152:153], v[88:89]
	v_pk_add_f32 v[90:91], v[154:155], v[90:91]
	v_pk_add_f32 v[88:89], v[156:157], v[88:89]
	v_pk_add_f32 v[90:91], v[158:159], v[90:91]
	v_pk_add_f32 v[88:89], v[160:161], v[88:89]
	v_pk_add_f32 v[90:91], v[162:163], v[90:91]
	v_pk_add_f32 v[88:89], v[164:165], v[88:89]
	v_pk_add_f32 v[90:91], v[166:167], v[90:91]
	v_pk_add_f32 v[88:89], v[168:169], v[88:89]
	v_pk_add_f32 v[90:91], v[170:171], v[90:91]
	v_pk_add_f32 v[88:89], v[172:173], v[88:89]
	v_pk_add_f32 v[90:91], v[174:175], v[90:91]
	v_pk_add_f32 v[88:89], v[176:177], v[88:89]
	v_pk_add_f32 v[90:91], v[178:179], v[90:91]
	v_pk_add_f32 v[88:89], v[180:181], v[88:89]
	v_pk_add_f32 v[90:91], v[182:183], v[90:91]
	v_pk_add_f32 v[88:89], v[184:185], v[88:89]
	v_pk_add_f32 v[90:91], v[186:187], v[90:91]
	v_pk_add_f32 v[86:87], v[190:191], v[90:91]
	v_pk_add_f32 v[84:85], v[188:189], v[88:89]
	s_andn2_saveexec_b64 s[4:5], s[4:5]
	s_cbranch_execz .LBB0_2513
	s_branch .LBB0_2512

.LBB0_2513:
	s_or_b64 exec, exec, s[4:5]
	s_and_saveexec_b64 s[4:5], s[0:1]
	s_xor_b64 s[4:5], exec, s[4:5]
	s_cbranch_execz .LBB0_2515
	v_or_b32_e32 v88, 0x600, v106
	v_mov_b32_e32 v89, v107
	v_lshl_add_u64 v[90:91], v[88:89], 1, s[82:83]
	global_load_dwordx2 v[90:91], v[90:91], off
	v_lshl_add_u64 v[110:111], v[88:89], 2, s[84:85]
	global_load_dwordx4 v[148:151], v[110:111], off
	v_add_co_u32_e32 v146, vcc, s12, v110
	s_nop 1
	v_addc_co_u32_e32 v147, vcc, 0, v111, vcc
	global_load_dwordx4 v[152:155], v[146:147], off
	v_add_co_u32_e32 v146, vcc, s13, v110
	s_nop 1
	v_addc_co_u32_e32 v147, vcc, 0, v111, vcc
	global_load_dwordx4 v[156:159], v[146:147], off
	v_add_co_u32_e32 v146, vcc, s14, v110
	s_nop 1
	v_addc_co_u32_e32 v147, vcc, 0, v111, vcc
	global_load_dwordx4 v[160:163], v[146:147], off
	v_add_co_u32_e32 v146, vcc, s15, v110
	s_nop 1
	v_addc_co_u32_e32 v147, vcc, 0, v111, vcc
	global_load_dwordx4 v[164:167], v[146:147], off
	v_add_co_u32_e32 v146, vcc, s16, v110
	s_nop 1
	v_addc_co_u32_e32 v147, vcc, 0, v111, vcc
	global_load_dwordx4 v[168:171], v[146:147], off
	v_add_co_u32_e32 v146, vcc, s17, v110
	s_nop 1
	v_addc_co_u32_e32 v147, vcc, 0, v111, vcc
	global_load_dwordx4 v[172:175], v[146:147], off
	v_add_co_u32_e32 v146, vcc, s18, v110
	s_nop 1
	v_addc_co_u32_e32 v147, vcc, 0, v111, vcc
	global_load_dwordx4 v[176:179], v[146:147], off
	v_add_co_u32_e32 v146, vcc, s19, v110
	s_nop 1
	v_addc_co_u32_e32 v147, vcc, 0, v111, vcc
	global_load_dwordx4 v[180:183], v[146:147], off
	v_add_co_u32_e32 v146, vcc, s20, v110
	s_nop 1
	v_addc_co_u32_e32 v147, vcc, 0, v111, vcc
	global_load_dwordx4 v[184:187], v[146:147], off
	v_add_co_u32_e32 v146, vcc, 0x1400000, v110
	s_nop 1
	v_addc_co_u32_e32 v147, vcc, 0, v111, vcc
	global_load_dwordx4 v[188:191], v[146:147], off
	s_waitcnt vmcnt(0)
	v_lshlrev_b32_e32 v92, 16, v90
	v_and_b32_e32 v93, 0xffff0000, v90
	v_lshlrev_b32_e32 v94, 16, v91
	v_and_b32_e32 v95, 0xffff0000, v91
	v_pk_fma_f32 v[92:93], v[92:93], s[92:93], v[148:149] op_sel_hi:[1,0,1]
	v_pk_fma_f32 v[94:95], v[94:95], s[92:93], v[150:151] op_sel_hi:[1,0,1]
	v_pk_add_f32 v[92:93], v[152:153], v[92:93]
	v_pk_add_f32 v[94:95], v[154:155], v[94:95]
	v_pk_add_f32 v[92:93], v[156:157], v[92:93]
	v_pk_add_f32 v[94:95], v[158:159], v[94:95]
	v_pk_add_f32 v[92:93], v[160:161], v[92:93]
	v_pk_add_f32 v[94:95], v[162:163], v[94:95]
	v_pk_add_f32 v[92:93], v[164:165], v[92:93]
	v_pk_add_f32 v[94:95], v[166:167], v[94:95]
	v_pk_add_f32 v[92:93], v[168:169], v[92:93]
	v_pk_add_f32 v[94:95], v[170:171], v[94:95]
	v_pk_add_f32 v[92:93], v[172:173], v[92:93]
	v_pk_add_f32 v[94:95], v[174:175], v[94:95]
	v_pk_add_f32 v[92:93], v[176:177], v[92:93]
	v_pk_add_f32 v[94:95], v[178:179], v[94:95]
	v_pk_add_f32 v[92:93], v[180:181], v[92:93]
	v_pk_add_f32 v[94:95], v[182:183], v[94:95]
	v_pk_add_f32 v[92:93], v[184:185], v[92:93]
	v_pk_add_f32 v[94:95], v[186:187], v[94:95]
	v_pk_add_f32 v[90:91], v[190:191], v[94:95]
	v_pk_add_f32 v[88:89], v[188:189], v[92:93]
	s_andn2_saveexec_b64 s[4:5], s[4:5]
	s_cbranch_execz .LBB0_2517
	s_branch .LBB0_2516

.LBB0_2517:
	s_or_b64 exec, exec, s[4:5]
	s_and_saveexec_b64 s[4:5], s[0:1]
	s_xor_b64 s[0:1], exec, s[4:5]
	s_cbranch_execz .LBB0_2519
	v_or_b32_e32 v106, 0x700, v106
	v_lshl_add_u64 v[92:93], v[106:107], 1, s[82:83]
	global_load_dwordx2 v[92:93], v[92:93], off
	v_lshl_add_u64 v[106:107], v[106:107], 2, s[84:85]
	global_load_dwordx4 v[148:151], v[106:107], off
	v_add_co_u32_e32 v146, vcc, s12, v106
	s_nop 1
	v_addc_co_u32_e32 v147, vcc, 0, v107, vcc
	global_load_dwordx4 v[152:155], v[146:147], off
	v_add_co_u32_e32 v146, vcc, s13, v106
	s_nop 1
	v_addc_co_u32_e32 v147, vcc, 0, v107, vcc
	global_load_dwordx4 v[156:159], v[146:147], off
	v_add_co_u32_e32 v146, vcc, s14, v106
	s_nop 1
	v_addc_co_u32_e32 v147, vcc, 0, v107, vcc
	global_load_dwordx4 v[160:163], v[146:147], off
	v_add_co_u32_e32 v146, vcc, s15, v106
	s_nop 1
	v_addc_co_u32_e32 v147, vcc, 0, v107, vcc
	global_load_dwordx4 v[164:167], v[146:147], off
	v_add_co_u32_e32 v146, vcc, s16, v106
	s_nop 1
	v_addc_co_u32_e32 v147, vcc, 0, v107, vcc
	global_load_dwordx4 v[168:171], v[146:147], off
	v_add_co_u32_e32 v146, vcc, s17, v106
	s_nop 1
	v_addc_co_u32_e32 v147, vcc, 0, v107, vcc
	global_load_dwordx4 v[172:175], v[146:147], off
	v_add_co_u32_e32 v146, vcc, s18, v106
	s_nop 1
	v_addc_co_u32_e32 v147, vcc, 0, v107, vcc
	global_load_dwordx4 v[176:179], v[146:147], off
	v_add_co_u32_e32 v146, vcc, s19, v106
	s_nop 1
	v_addc_co_u32_e32 v147, vcc, 0, v107, vcc
	global_load_dwordx4 v[180:183], v[146:147], off
	v_add_co_u32_e32 v146, vcc, s20, v106
	s_nop 1
	v_addc_co_u32_e32 v147, vcc, 0, v107, vcc
	global_load_dwordx4 v[184:187], v[146:147], off
	v_add_co_u32_e32 v146, vcc, 0x1400000, v106
	s_nop 1
	v_addc_co_u32_e32 v147, vcc, 0, v107, vcc
	global_load_dwordx4 v[188:191], v[146:147], off
	s_waitcnt vmcnt(0)
	v_lshlrev_b32_e32 v108, 16, v92
	v_and_b32_e32 v109, 0xffff0000, v92
	v_lshlrev_b32_e32 v110, 16, v93
	v_and_b32_e32 v111, 0xffff0000, v93
	v_pk_fma_f32 v[108:109], v[108:109], s[92:93], v[148:149] op_sel_hi:[1,0,1]
	v_pk_fma_f32 v[110:111], v[110:111], s[92:93], v[150:151] op_sel_hi:[1,0,1]
	v_pk_add_f32 v[108:109], v[152:153], v[108:109]
	v_pk_add_f32 v[110:111], v[154:155], v[110:111]
	v_pk_add_f32 v[108:109], v[156:157], v[108:109]
	v_pk_add_f32 v[110:111], v[158:159], v[110:111]
	v_pk_add_f32 v[108:109], v[160:161], v[108:109]
	v_pk_add_f32 v[110:111], v[162:163], v[110:111]
	v_pk_add_f32 v[108:109], v[164:165], v[108:109]
	v_pk_add_f32 v[110:111], v[166:167], v[110:111]
	v_pk_add_f32 v[108:109], v[168:169], v[108:109]
	v_pk_add_f32 v[110:111], v[170:171], v[110:111]
	v_pk_add_f32 v[108:109], v[172:173], v[108:109]
	v_pk_add_f32 v[110:111], v[174:175], v[110:111]
	v_pk_add_f32 v[108:109], v[176:177], v[108:109]
	v_pk_add_f32 v[110:111], v[178:179], v[110:111]
	v_pk_add_f32 v[108:109], v[180:181], v[108:109]
	v_pk_add_f32 v[110:111], v[182:183], v[110:111]
	v_pk_add_f32 v[108:109], v[184:185], v[108:109]
	v_pk_add_f32 v[110:111], v[186:187], v[110:111]
	v_pk_add_f32 v[94:95], v[190:191], v[110:111]
	v_pk_add_f32 v[92:93], v[188:189], v[108:109]
	s_andn2_saveexec_b64 s[0:1], s[0:1]
	s_cbranch_execnz .LBB0_2520
	s_branch .LBB0_2521
